# phase_out epilogue: 20 X loads hoisted (12 before last k-step, 8 after), counted vmcnt
# speedup vs baseline: 1.0034x; 1.0034x over previous
.LBB0_582:
	s_add_i32 s7, s5, 1
	s_bitcmp1_b32 s7, 0
	s_cselect_b32 s13, 0x9000, 0
	v_add_u32_e32 v106, s13, v92
	v_lshl_add_u64 v[102:103], v[88:89], 0, s[8:9]
	s_mov_b64 s[14:15], 0x1c9b1080
	v_readfirstlane_b32 s13, v106
	v_add_u32_e32 v107, 0x1000, v106
	v_lshl_add_u64 v[104:105], v[102:103], 0, s[14:15]
	s_mov_b32 m0, s13
	s_mov_b64 s[14:15], 0x1c9c1080
	v_readfirstlane_b32 s13, v107
	v_add_u32_e32 v107, 0x2000, v106
	global_load_lds_dwordx4 v[104:105], off
	v_lshl_add_u64 v[104:105], v[102:103], 0, s[14:15]
	s_mov_b32 m0, s13
	s_mov_b64 s[14:15], 0x1c9d1080
	v_readfirstlane_b32 s13, v107
	v_add_u32_e32 v107, 0x3000, v106
	global_load_lds_dwordx4 v[104:105], off
	v_lshl_add_u64 v[104:105], v[102:103], 0, s[14:15]
	s_mov_b32 m0, s13
	s_mov_b64 s[14:15], 0x1c9e1080
	v_readfirstlane_b32 s13, v107
	global_load_lds_dwordx4 v[104:105], off
	v_lshl_add_u64 v[104:105], v[102:103], 0, s[14:15]
	s_mov_b32 m0, s13
	s_mov_b64 s[14:15], 0x1c9f1080
	global_load_lds_dwordx4 v[104:105], off
	v_add_u32_e32 v104, 0x4000, v106
	v_lshl_add_u64 v[102:103], v[102:103], 0, s[14:15]
	v_readfirstlane_b32 s13, v104
	s_mov_b32 m0, s13
	v_add_u32_e32 v107, 0x5000, v106
	global_load_lds_dwordx4 v[102:103], off
	v_lshl_add_u64 v[102:103], v[90:91], 0, s[8:9]
	s_mov_b64 s[14:15], 0x14b31080
	v_readfirstlane_b32 s13, v107
	v_add_u32_e32 v107, 0x6000, v106
	v_lshl_add_u64 v[104:105], v[102:103], 0, s[14:15]
	s_mov_b32 m0, s13
	s_mov_b64 s[14:15], 0x14b41080
	v_readfirstlane_b32 s13, v107
	v_add_u32_e32 v107, 0x7000, v106
	global_load_lds_dwordx4 v[104:105], off
	v_lshl_add_u64 v[104:105], v[102:103], 0, s[14:15]
	s_mov_b32 m0, s13
	s_mov_b64 s[14:15], 0x14b51080
	v_readfirstlane_b32 s13, v107
	global_load_lds_dwordx4 v[104:105], off
	v_lshl_add_u64 v[104:105], v[102:103], 0, s[14:15]
	s_mov_b32 m0, s13
	s_mov_b64 s[14:15], 0x14b61080
	global_load_lds_dwordx4 v[104:105], off
	v_add_u32_e32 v104, 0x8000, v106
	v_lshl_add_u64 v[102:103], v[102:103], 0, s[14:15]
	v_readfirstlane_b32 s13, v104
	s_mov_b32 m0, s13
	s_bitcmp1_b32 s5, 0
	global_load_lds_dwordx4 v[102:103], off
	s_cselect_b32 s5, 0x9000, 0
	s_add_i32 s5, s5, 0
	v_add_u32_e32 v118, s5, v93
	v_add_u32_e32 v119, v118, v94
	v_add_u32_e32 v156, v118, v95
	ds_read_b128 v[102:105], v119
	ds_read_b128 v[106:109], v119 offset:2048
	ds_read_b128 v[110:113], v119 offset:4096
	ds_read_b128 v[114:117], v119 offset:6144
	ds_read_b128 v[118:121], v119 offset:8192
	ds_read_b128 v[122:125], v156 offset:20480
	ds_read_b128 v[126:129], v156 offset:22528
	ds_read_b128 v[130:133], v156 offset:24576
	ds_read_b128 v[156:159], v156 offset:26624
	s_setprio 1
	s_waitcnt lgkmcnt(0)
	v_mfma_f32_16x16x32_bf16 v[76:79], v[122:125], v[102:105], v[76:79]
	v_mfma_f32_16x16x32_bf16 v[72:75], v[126:129], v[102:105], v[72:75]
	v_mfma_f32_16x16x32_bf16 v[68:71], v[130:133], v[102:105], v[68:71]
	v_mfma_f32_16x16x32_bf16 v[64:67], v[156:159], v[102:105], v[64:67]
	v_mfma_f32_16x16x32_bf16 v[60:63], v[122:125], v[106:109], v[60:63]
	v_mfma_f32_16x16x32_bf16 v[56:59], v[126:129], v[106:109], v[56:59]
	v_mfma_f32_16x16x32_bf16 v[52:55], v[130:133], v[106:109], v[52:55]
	v_mfma_f32_16x16x32_bf16 v[48:51], v[156:159], v[106:109], v[48:51]
	v_mfma_f32_16x16x32_bf16 v[44:47], v[122:125], v[110:113], v[44:47]
	v_mfma_f32_16x16x32_bf16 v[40:43], v[126:129], v[110:113], v[40:43]
	v_mfma_f32_16x16x32_bf16 v[36:39], v[130:133], v[110:113], v[36:39]
	v_mfma_f32_16x16x32_bf16 v[32:35], v[156:159], v[110:113], v[32:35]
	v_mfma_f32_16x16x32_bf16 v[28:31], v[122:125], v[114:117], v[28:31]
	v_mfma_f32_16x16x32_bf16 v[24:27], v[126:129], v[114:117], v[24:27]
	v_mfma_f32_16x16x32_bf16 v[20:23], v[130:133], v[114:117], v[20:23]
	v_mfma_f32_16x16x32_bf16 v[16:19], v[156:159], v[114:117], v[16:19]
	v_mfma_f32_16x16x32_bf16 v[12:15], v[122:125], v[118:121], v[12:15]
	v_mfma_f32_16x16x32_bf16 v[8:11], v[126:129], v[118:121], v[8:11]
	v_mfma_f32_16x16x32_bf16 v[4:7], v[130:133], v[118:121], v[4:7]
	v_mfma_f32_16x16x32_bf16 v[0:3], v[156:159], v[118:121], v[0:3]
	s_setprio 0
	v_add_u32_e32 v118, s5, v96
	v_add_u32_e32 v119, v118, v94
	v_add_u32_e32 v156, v118, v95
	ds_read_b128 v[102:105], v119
	ds_read_b128 v[106:109], v119 offset:2048
	ds_read_b128 v[110:113], v119 offset:4096
	ds_read_b128 v[114:117], v119 offset:6144
	ds_read_b128 v[118:121], v119 offset:8192
	ds_read_b128 v[122:125], v156 offset:20480
	ds_read_b128 v[126:129], v156 offset:22528
	ds_read_b128 v[130:133], v156 offset:24576
	ds_read_b128 v[156:159], v156 offset:26624
	s_setprio 1
	s_waitcnt lgkmcnt(0)
	v_mfma_f32_16x16x32_bf16 v[76:79], v[122:125], v[102:105], v[76:79]
	v_mfma_f32_16x16x32_bf16 v[72:75], v[126:129], v[102:105], v[72:75]
	v_mfma_f32_16x16x32_bf16 v[68:71], v[130:133], v[102:105], v[68:71]
	v_mfma_f32_16x16x32_bf16 v[64:67], v[156:159], v[102:105], v[64:67]
	v_mfma_f32_16x16x32_bf16 v[60:63], v[122:125], v[106:109], v[60:63]
	v_mfma_f32_16x16x32_bf16 v[56:59], v[126:129], v[106:109], v[56:59]
	v_mfma_f32_16x16x32_bf16 v[52:55], v[130:133], v[106:109], v[52:55]
	v_mfma_f32_16x16x32_bf16 v[48:51], v[156:159], v[106:109], v[48:51]
	v_mfma_f32_16x16x32_bf16 v[44:47], v[122:125], v[110:113], v[44:47]
	v_mfma_f32_16x16x32_bf16 v[40:43], v[126:129], v[110:113], v[40:43]
	v_mfma_f32_16x16x32_bf16 v[36:39], v[130:133], v[110:113], v[36:39]
	v_mfma_f32_16x16x32_bf16 v[32:35], v[156:159], v[110:113], v[32:35]
	v_mfma_f32_16x16x32_bf16 v[28:31], v[122:125], v[114:117], v[28:31]
	v_mfma_f32_16x16x32_bf16 v[24:27], v[126:129], v[114:117], v[24:27]
	v_mfma_f32_16x16x32_bf16 v[20:23], v[130:133], v[114:117], v[20:23]
	v_mfma_f32_16x16x32_bf16 v[16:19], v[156:159], v[114:117], v[16:19]
	v_mfma_f32_16x16x32_bf16 v[12:15], v[122:125], v[118:121], v[12:15]
	v_mfma_f32_16x16x32_bf16 v[8:11], v[126:129], v[118:121], v[8:11]
	v_mfma_f32_16x16x32_bf16 v[4:7], v[130:133], v[118:121], v[4:7]
	v_mfma_f32_16x16x32_bf16 v[0:3], v[156:159], v[118:121], v[0:3]
	s_setprio 0
	s_waitcnt vmcnt(0)
	s_add_u32 s8, s8, 0x80
	s_addc_u32 s9, s9, 0
	s_cmpk_lg_i32 s8, 0x780
	s_mov_b32 s5, s7
	s_waitcnt vmcnt(0)
	s_barrier
	s_cbranch_scc1 .LBB0_582
	v_add_u32_e32 v232, v97, v176
	v_lshrrev_b32_e32 v233, 2, v232
	v_ashrrev_i32_e32 v234, 7, v232
	v_and_b32_e32 v236, 64, v232
	v_and_b32_e32 v233, 12, v233
	v_and_or_b32 v248, v232, 15, s6
	s_movk_i32 s5, 0x50
	s_lshl_b32 s4, s4, 7
	v_mad_u32_u24 v248, v234, s5, v248
	v_or3_b32 v236, v236, v233, s4
	v_ashrrev_i32_e32 v249, 31, v248
	v_lshlrev_b64 v[248:249], 12, v[248:249]
	v_lshl_add_u64 v[248:249], s[0:1], 0, v[248:249]
	v_ashrrev_i32_e32 v237, 31, v236
	v_lshl_add_u64 v[248:249], v[236:237], 2, v[248:249]
	s_mov_b64 s[4:5], 0x10000
	v_lshl_add_u64 v[246:247], v[248:249], 0, s[4:5]
	s_mov_b64 s[4:5], 0x20000
	v_lshl_add_u64 v[244:245], v[248:249], 0, s[4:5]
	s_mov_b64 s[4:5], 0x30000
	v_lshl_add_u64 v[242:243], v[248:249], 0, s[4:5]
	s_mov_b64 s[4:5], 0x40000
	v_lshl_add_u64 v[240:241], v[248:249], 0, s[4:5]
	global_load_dwordx4 v[178:181], v[248:249], off
	global_load_dwordx4 v[182:185], v[248:249], off offset:64
	global_load_dwordx4 v[186:189], v[248:249], off offset:128
	global_load_dwordx4 v[190:193], v[248:249], off offset:192
	global_load_dwordx4 v[194:197], v[246:247], off
	global_load_dwordx4 v[198:201], v[246:247], off offset:64
	global_load_dwordx4 v[206:209], v[246:247], off offset:128
	global_load_dwordx4 v[210:213], v[246:247], off offset:192
	global_load_dwordx4 v[214:217], v[244:245], off
	global_load_dwordx4 v[218:221], v[244:245], off offset:64
	global_load_dwordx4 v[222:225], v[244:245], off offset:128
	global_load_dwordx4 v[226:229], v[244:245], off offset:192
	v_add_u32_e32 v110, v100, v95
	v_add_u32_e32 v130, v100, v94
	ds_read_b128 v[88:91], v110 offset:63488
	ds_read_b128 v[102:105], v110 offset:61440
	ds_read_b128 v[106:109], v110 offset:59392
	ds_read_b128 v[110:113], v110 offset:57344
	ds_read_b128 v[114:117], v130 offset:45056
	ds_read_b128 v[118:121], v130 offset:43008
	ds_read_b128 v[122:125], v130 offset:40960
	ds_read_b128 v[126:129], v130 offset:38912
	ds_read_b128 v[130:133], v130 offset:36864
	s_setprio 1
	s_waitcnt lgkmcnt(0)
	v_mfma_f32_16x16x32_bf16 v[76:79], v[110:113], v[130:133], v[76:79]
	v_mfma_f32_16x16x32_bf16 v[72:75], v[106:109], v[130:133], v[72:75]
	v_mfma_f32_16x16x32_bf16 v[68:71], v[102:105], v[130:133], v[68:71]
	v_mfma_f32_16x16x32_bf16 v[64:67], v[88:91], v[130:133], v[64:67]
	v_mfma_f32_16x16x32_bf16 v[60:63], v[110:113], v[126:129], v[60:63]
	v_mfma_f32_16x16x32_bf16 v[56:59], v[106:109], v[126:129], v[56:59]
	v_mfma_f32_16x16x32_bf16 v[52:55], v[102:105], v[126:129], v[52:55]
	v_mfma_f32_16x16x32_bf16 v[48:51], v[88:91], v[126:129], v[48:51]
	v_mfma_f32_16x16x32_bf16 v[44:47], v[110:113], v[122:125], v[44:47]
	v_mfma_f32_16x16x32_bf16 v[40:43], v[106:109], v[122:125], v[40:43]
	v_mfma_f32_16x16x32_bf16 v[36:39], v[102:105], v[122:125], v[36:39]
	v_mfma_f32_16x16x32_bf16 v[32:35], v[88:91], v[122:125], v[32:35]
	v_mfma_f32_16x16x32_bf16 v[28:31], v[110:113], v[118:121], v[28:31]
	v_mfma_f32_16x16x32_bf16 v[24:27], v[106:109], v[118:121], v[24:27]
	v_mfma_f32_16x16x32_bf16 v[20:23], v[102:105], v[118:121], v[20:23]
	v_mfma_f32_16x16x32_bf16 v[16:19], v[88:91], v[118:121], v[16:19]
	v_mfma_f32_16x16x32_bf16 v[12:15], v[110:113], v[114:117], v[12:15]
	v_mfma_f32_16x16x32_bf16 v[8:11], v[106:109], v[114:117], v[8:11]
	v_mfma_f32_16x16x32_bf16 v[4:7], v[102:105], v[114:117], v[4:7]
	v_mfma_f32_16x16x32_bf16 v[0:3], v[88:91], v[114:117], v[0:3]
	s_setprio 0
	v_add_u32_e32 v114, v101, v94
	v_add_u32_e32 v130, v101, v95
	ds_read_b128 v[88:91], v114 offset:36864
	ds_read_b128 v[102:105], v114 offset:38912
	ds_read_b128 v[106:109], v114 offset:40960
	ds_read_b128 v[110:113], v114 offset:43008
	ds_read_b128 v[114:117], v114 offset:45056
	ds_read_b128 v[118:121], v130 offset:57344
	ds_read_b128 v[122:125], v130 offset:59392
	ds_read_b128 v[126:129], v130 offset:61440
	ds_read_b128 v[130:133], v130 offset:63488
	s_setprio 1
	s_waitcnt lgkmcnt(3)
	v_mfma_f32_16x16x32_bf16 v[76:79], v[118:121], v[88:91], v[76:79]
	s_waitcnt lgkmcnt(2)
	v_mfma_f32_16x16x32_bf16 v[72:75], v[122:125], v[88:91], v[72:75]
	s_waitcnt lgkmcnt(1)
	v_mfma_f32_16x16x32_bf16 v[68:71], v[126:129], v[88:91], v[68:71]
	s_waitcnt lgkmcnt(0)
	v_mfma_f32_16x16x32_bf16 v[64:67], v[130:133], v[88:91], v[64:67]
	v_mfma_f32_16x16x32_bf16 v[60:63], v[118:121], v[102:105], v[60:63]
	v_mfma_f32_16x16x32_bf16 v[56:59], v[122:125], v[102:105], v[56:59]
	v_mfma_f32_16x16x32_bf16 v[88:91], v[126:129], v[102:105], v[52:55]
	v_mfma_f32_16x16x32_bf16 v[48:51], v[130:133], v[102:105], v[48:51]
	v_mfma_f32_16x16x32_bf16 v[44:47], v[118:121], v[106:109], v[44:47]
	v_mfma_f32_16x16x32_bf16 v[40:43], v[122:125], v[106:109], v[40:43]
	v_mfma_f32_16x16x32_bf16 v[36:39], v[126:129], v[106:109], v[36:39]
	v_mfma_f32_16x16x32_bf16 v[32:35], v[130:133], v[106:109], v[32:35]
	v_mfma_f32_16x16x32_bf16 v[28:31], v[118:121], v[110:113], v[28:31]
	v_mfma_f32_16x16x32_bf16 v[24:27], v[122:125], v[110:113], v[24:27]
	v_mfma_f32_16x16x32_bf16 v[20:23], v[126:129], v[110:113], v[20:23]
	v_mfma_f32_16x16x32_bf16 v[16:19], v[130:133], v[110:113], v[16:19]
	v_mfma_f32_16x16x32_bf16 v[12:15], v[118:121], v[114:117], v[12:15]
	v_mfma_f32_16x16x32_bf16 v[8:11], v[122:125], v[114:117], v[8:11]
	v_mfma_f32_16x16x32_bf16 v[4:7], v[126:129], v[114:117], v[4:7]
	v_mfma_f32_16x16x32_bf16 v[0:3], v[130:133], v[114:117], v[0:3]
	s_setprio 0
	global_load_dwordx4 v[102:105], v[242:243], off
	global_load_dwordx4 v[106:109], v[242:243], off offset:64
	global_load_dwordx4 v[110:113], v[242:243], off offset:128
	global_load_dwordx4 v[114:117], v[242:243], off offset:192
	global_load_dwordx4 v[118:121], v[240:241], off
	global_load_dwordx4 v[122:125], v[240:241], off offset:64
	global_load_dwordx4 v[126:129], v[240:241], off offset:128
	global_load_dwordx4 v[130:133], v[240:241], off offset:192
	s_barrier
	s_mov_b32 s8, 0
	s_waitcnt vmcnt(19)
	v_pk_add_f32 v[76:77], v[76:77], v[178:179]
	v_pk_add_f32 v[78:79], v[78:79], v[180:181]
	global_store_dwordx4 v[248:249], v[76:79], off
	s_waitcnt vmcnt(19)
	v_pk_add_f32 v[72:73], v[72:73], v[182:183]
	v_pk_add_f32 v[74:75], v[74:75], v[184:185]
	global_store_dwordx4 v[248:249], v[72:75], off offset:64
	s_waitcnt vmcnt(19)
	v_pk_add_f32 v[68:69], v[68:69], v[186:187]
	v_pk_add_f32 v[70:71], v[70:71], v[188:189]
	global_store_dwordx4 v[248:249], v[68:71], off offset:128
	s_waitcnt vmcnt(19)
	v_pk_add_f32 v[64:65], v[64:65], v[190:191]
	v_pk_add_f32 v[66:67], v[66:67], v[192:193]
	global_store_dwordx4 v[248:249], v[64:67], off offset:192
	s_waitcnt vmcnt(19)
	v_pk_add_f32 v[60:61], v[60:61], v[194:195]
	v_pk_add_f32 v[62:63], v[62:63], v[196:197]
	global_store_dwordx4 v[246:247], v[60:63], off
	s_waitcnt vmcnt(19)
	v_pk_add_f32 v[56:57], v[56:57], v[198:199]
	v_pk_add_f32 v[58:59], v[58:59], v[200:201]
	global_store_dwordx4 v[246:247], v[56:59], off offset:64
	s_waitcnt vmcnt(19)
	v_pk_add_f32 v[88:89], v[88:89], v[206:207]
	v_pk_add_f32 v[90:91], v[90:91], v[208:209]
	global_store_dwordx4 v[246:247], v[88:91], off offset:128
	s_waitcnt vmcnt(19)
	v_pk_add_f32 v[48:49], v[48:49], v[210:211]
	v_pk_add_f32 v[50:51], v[50:51], v[212:213]
	global_store_dwordx4 v[246:247], v[48:51], off offset:192
	s_waitcnt vmcnt(19)
	v_pk_add_f32 v[44:45], v[44:45], v[214:215]
	v_pk_add_f32 v[46:47], v[46:47], v[216:217]
	global_store_dwordx4 v[244:245], v[44:47], off
	s_waitcnt vmcnt(19)
	v_pk_add_f32 v[40:41], v[40:41], v[218:219]
	v_pk_add_f32 v[42:43], v[42:43], v[220:221]
	global_store_dwordx4 v[244:245], v[40:43], off offset:64
	s_waitcnt vmcnt(19)
	v_pk_add_f32 v[36:37], v[36:37], v[222:223]
	v_pk_add_f32 v[38:39], v[38:39], v[224:225]
	global_store_dwordx4 v[244:245], v[36:39], off offset:128
	s_waitcnt vmcnt(19)
	v_pk_add_f32 v[32:33], v[32:33], v[226:227]
	v_pk_add_f32 v[34:35], v[34:35], v[228:229]
	global_store_dwordx4 v[244:245], v[32:35], off offset:192
	s_waitcnt vmcnt(19)
	v_pk_add_f32 v[28:29], v[28:29], v[102:103]
	v_pk_add_f32 v[30:31], v[30:31], v[104:105]
	global_store_dwordx4 v[242:243], v[28:31], off
	s_waitcnt vmcnt(19)
	v_pk_add_f32 v[24:25], v[24:25], v[106:107]
	v_pk_add_f32 v[26:27], v[26:27], v[108:109]
	global_store_dwordx4 v[242:243], v[24:27], off offset:64
	s_waitcnt vmcnt(19)
	v_pk_add_f32 v[20:21], v[20:21], v[110:111]
	v_pk_add_f32 v[22:23], v[22:23], v[112:113]
	global_store_dwordx4 v[242:243], v[20:23], off offset:128
	s_waitcnt vmcnt(19)
	v_pk_add_f32 v[16:17], v[16:17], v[114:115]
	v_pk_add_f32 v[18:19], v[18:19], v[116:117]
	global_store_dwordx4 v[242:243], v[16:19], off offset:192
	s_waitcnt vmcnt(19)
	v_pk_add_f32 v[12:13], v[12:13], v[118:119]
	v_pk_add_f32 v[14:15], v[14:15], v[120:121]
	global_store_dwordx4 v[240:241], v[12:15], off
	s_waitcnt vmcnt(19)
	v_pk_add_f32 v[8:9], v[8:9], v[122:123]
	v_pk_add_f32 v[10:11], v[10:11], v[124:125]
	global_store_dwordx4 v[240:241], v[8:11], off offset:64
	s_waitcnt vmcnt(19)
	v_pk_add_f32 v[4:5], v[4:5], v[126:127]
	v_pk_add_f32 v[6:7], v[6:7], v[128:129]
	global_store_dwordx4 v[240:241], v[4:7], off offset:128
	s_waitcnt vmcnt(19)
	v_pk_add_f32 v[0:1], v[0:1], v[130:131]
	v_pk_add_f32 v[2:3], v[2:3], v[132:133]
	global_store_dwordx4 v[240:241], v[0:3], off offset:192
